# GEMM unit loop: next-tile index via shifts and masks (nM=64, WGM=8, nwg%8==0 make the divisions exact bit fields) instead of the emulated integer divisions
# speedup vs baseline: 1.0045x; 1.0009x over previous
;     __host__ __device__ bool next(int i, Unit& u) const {
;         const long L = (long)i * G + c; if (L >= nwg) return false;
;         int wgid = (int)L; { const int q = nwg / NXCD, r = nwg % NXCD, xcd = wgid % NXCD, off = wgid / NXCD; wgid = (xcd < r ? xcd * (q + 1) : r * (q + 1) + (xcd - r) * q) + off; }
;         const int nig = WGM * nN, gid = wgid / nig, fm = gid * WGM, gsz = (nM - fm) < WGM ? (nM - fm) : WGM;
;         u.pm = fm + ((wgid % nig) % gsz); u.pn = (wgid % nig) / gsz; return true;
;     }
.LBB0_315:
	s_add_i32 s71, s71, 1
	s_mul_i32 s12, s71, s26
	s_mul_hi_u32 s13, s71, s58
	s_add_i32 s13, s13, s12
	s_mul_i32 s12, s71, s58
	s_add_u32 s12, s12, s2
	s_addc_u32 s13, s13, s91
	v_mov_b64_e32 v[2:3], s[0:1]
	v_cmp_ge_i64_e32 vcc, s[12:13], v[2:3]
	v_cmp_lt_i64_e64 s[42:43], s[12:13], v[2:3]
	s_cbranch_vccnz .LBB0_317
	s_and_b32 s40, s12, 7
	s_lshl_b32 s40, s40, 3
	s_bfe_u32 s41, s12, 0x30003
	s_add_i32 s74, s40, s41
	s_lshr_b32 s69, s12, 6
